# rope
# speedup vs baseline: 1.0050x; 1.0050x over previous
; DEVI void phase2(const Params& p, char* shm) {
;     ...
;       auto ep = [&](Acc256& acc) {
;         EPI_IDX;
; #pragma unroll
;         for (int ai = 0; ai < 2; ++ai)
; #pragma unroll
;           for (int m = 0; m < 4; ++m) {
;             int rl = ai * 128 + wr * 64 + m * 16 + fr;
;             float rs = rsb[rl];
;             int row = brow + rl;
;             int pos = row & 4095;
; #pragma unroll
;             for (int bj = 0; bj < 2; ++bj) {
;               int cA = bcol + bj * 128 + wc * 32;
;               bool isrope = (cA % 96) == 64;
;               f32x4 va = acc[ai][bj][m][0], vb = acc[ai][bj][m][1];
;               float oa[4], ob[4];
; #pragma unroll
;               for (int j = 0; j < 4; ++j) {
;                 float x1 = va[j] * rs, x2 = vb[j] * rs;
;                 if (isrope) {
;                   float2 cs = tab[pos * 16 + fq * 4 + j];
;                   oa[j] = x1 * cs.x - x2 * cs.y;
;                   ob[j] = x1 * cs.y + x2 * cs.x;
;                 } else {
;                   oa[j] = x1;
;                   ob[j] = x2;
;                 }
;               }
;               uint2 pa, pb;
;               pa.x = pack2(oa[0], oa[1]); pa.y = pack2(oa[2], oa[3]);
;               pb.x = pack2(ob[0], ob[1]); pb.y = pack2(ob[2], ob[3]);
;               *reinterpret_cast<uint4*>(Qb + (size_t)row * 768 + cA + (fq & 1) * 16 + (fq >> 1) * 8) = widen_pair(pa, pb);
;             }
.LBB0_536:
	s_or_b64 exec, exec, s[2:3]
	v_mov_b32_e32 v128, v214
	s_movk_i32 s2, 0xffc0
	v_and_b32_e32 v130, 15, v128
	v_ashrrev_i32_e32 v131, 2, v128
	v_and_or_b32 v146, v131, s2, v130
	v_lshrrev_b32_e32 v130, 1, v128
	v_and_b32_e32 v131, 0x60, v130
	v_lshl_add_u32 v130, v146, 2, 0
	v_add_u32_e32 v143, 0x20000, v130
	ds_read_b32 v130, v143
	v_or_b32_e32 v148, s44, v131
	s_movk_i32 s2, 0xaaab
	v_mad_legacy_u16 v131, v148, s2, v142
	v_lshlrev_b16_e32 v132, 11, v131
	v_lshrrev_b16_e32 v131, 5, v131
	v_or_b32_e32 v131, v131, v132
	s_movk_i32 s2, 0x2a9
	v_mov_b32_e32 v132, v124
	v_mov_b32_e32 v133, v120
	v_cmp_lt_u16_e32 vcc, s2, v131
	s_waitcnt lgkmcnt(0)
	v_pk_mul_f32 v[132:133], v[132:133], v[130:131] op_sel_hi:[1,0]
	s_and_saveexec_b64 s[2:3], vcc
	s_xor_b64 s[2:3], exec, s[2:3]
	v_mov_b32_e32 v124, v133
	s_or_saveexec_b64 s[2:3], s[2:3]
	v_lshrrev_b32_e32 v149, 2, v128
	v_add_u32_e32 v145, s79, v146
	v_and_b32_e32 v144, 12, v149
	v_lshlrev_b32_e32 v120, 4, v145
	s_mov_b32 s6, 0xfcf0
	v_and_or_b32 v120, v120, s6, v144
	v_lshlrev_b32_e32 v147, 3, v120
	global_load_dwordx2 v[244:245], v147, s[22:23]
	global_load_dwordx2 v[246:247], v147, s[22:23] offset:8
	global_load_dwordx2 v[248:249], v147, s[22:23] offset:16
	global_load_dwordx2 v[250:251], v147, s[22:23] offset:24
	s_waitcnt vmcnt(0)
	s_xor_b64 exec, exec, s[2:3]
	s_cbranch_execz .LBB0_540
	v_mov_b32_e32 v134, v244
	v_mov_b32_e32 v135, v245
	v_pk_mul_f32 v[136:137], v[132:133], v[134:135] op_sel:[1,0] op_sel_hi:[0,1]
	v_pk_mul_f32 v[132:133], v[132:133], v[134:135]
	v_sub_f32_e32 v124, v136, v137
	v_add_f32_e32 v132, v132, v133
.LBB0_540:
	s_or_b64 exec, exec, s[2:3]
	v_mov_b32_e32 v131, v130
	v_mov_b32_e32 v120, v125
	v_pk_mul_f32 v[134:135], v[120:121], v[130:131]
	s_and_saveexec_b64 s[2:3], vcc
	s_xor_b64 s[2:3], exec, s[2:3]
	v_mov_b32_e32 v121, v135
	s_andn2_saveexec_b64 s[2:3], s[2:3]
	s_cbranch_execz .LBB0_544
	v_mov_b32_e32 v120, v246
	v_mov_b32_e32 v121, v247
	v_pk_mul_f32 v[136:137], v[134:135], v[120:121] op_sel:[1,0] op_sel_hi:[0,1]
	v_pk_mul_f32 v[120:121], v[134:135], v[120:121]
	s_nop 0
	v_add_f32_e32 v134, v120, v121
	v_sub_f32_e32 v121, v136, v137
.LBB0_544:
	s_or_b64 exec, exec, s[2:3]
	v_mov_b32_e32 v136, v126
	v_mov_b32_e32 v137, v122
	v_pk_mul_f32 v[136:137], v[136:137], v[130:131]
	s_and_saveexec_b64 s[2:3], vcc
	s_xor_b64 s[2:3], exec, s[2:3]
	s_andn2_saveexec_b64 s[2:3], s[2:3]
	s_cbranch_execz .LBB0_546
	v_mov_b32_e32 v150, v248
	v_mov_b32_e32 v151, v249
	v_pk_mul_f32 v[152:153], v[136:137], v[150:151] op_sel:[1,0] op_sel_hi:[0,1]
	v_pk_mul_f32 v[136:137], v[136:137], v[150:151]
	s_nop 0
	v_add_f32_e32 v136, v136, v137
	v_sub_f32_e32 v137, v152, v153
.LBB0_546:
	s_or_b64 exec, exec, s[2:3]
	v_mov_b32_e32 v122, v127
	v_pk_mul_f32 v[122:123], v[122:123], v[130:131]
	s_and_saveexec_b64 s[2:3], vcc
	s_xor_b64 s[2:3], exec, s[2:3]
	s_andn2_saveexec_b64 s[2:3], s[2:3]
	s_cbranch_execz .LBB0_548
	v_mov_b32_e32 v126, v250
	v_mov_b32_e32 v127, v251
	v_pk_mul_f32 v[150:151], v[122:123], v[126:127] op_sel:[1,0] op_sel_hi:[0,1]
	v_pk_mul_f32 v[122:123], v[122:123], v[126:127]
	s_nop 0
	v_add_f32_e32 v122, v122, v123
	v_sub_f32_e32 v123, v150, v151
.LBB0_548:
	s_or_b64 exec, exec, s[2:3]
	v_cvt_pk_bf16_f32 v150, v124, v121
	v_mov_b64_e32 v[120:121], s[40:41]
	v_and_b32_e32 v125, 16, v128
	v_mad_i64_i32 v[120:121], s[2:3], v145, s59, v[120:121]
	v_lshlrev_b32_e32 v128, 1, v148
	v_cvt_pk_bf16_f32 v151, v137, v123
	v_cvt_pk_bf16_f32 v153, v136, v122
	v_lshl_add_u64 v[122:123], v[120:121], 0, v[128:129]
	v_lshlrev_b32_e32 v120, 1, v125
	v_mov_b32_e32 v121, v129
	v_and_b32_e32 v126, 8, v149
	v_lshl_add_u64 v[124:125], v[122:123], 0, v[120:121]
	v_or_b32_e32 v121, 0x80, v148
	s_movk_i32 s2, 0xaaab
	v_lshlrev_b32_e32 v122, 1, v126
	v_mov_b32_e32 v123, v129
	v_mad_legacy_u16 v121, v121, s2, v142
	v_lshl_add_u64 v[124:125], v[124:125], 0, v[122:123]
	v_lshlrev_b16_e32 v123, 11, v121
	v_lshrrev_b16_e32 v121, 5, v121
	v_cvt_pk_bf16_f32 v152, v132, v134
	v_or_b32_e32 v121, v121, v123
	s_movk_i32 s2, 0x2a9
	v_mov_b32_e32 v126, v116
	v_mov_b32_e32 v127, v112
	v_permlane16_swap_b32_e32 v150, v152
	v_permlane16_swap_b32_e32 v151, v153
	v_cmp_lt_u16_e64 s[2:3], s2, v121
	v_pk_mul_f32 v[126:127], v[126:127], v[130:131]
	global_store_dwordx4 v[124:125], v[150:153], off
	s_and_saveexec_b64 s[44:45], s[2:3]
	s_xor_b64 s[44:45], exec, s[44:45]
	v_mov_b32_e32 v116, v127
	s_andn2_saveexec_b64 s[44:45], s[44:45]
	s_cbranch_execz .LBB0_552
	v_mov_b32_e32 v132, v244
	v_mov_b32_e32 v133, v245
	v_pk_mul_f32 v[134:135], v[126:127], v[132:133] op_sel:[1,0] op_sel_hi:[0,1]
	v_pk_mul_f32 v[126:127], v[126:127], v[132:133]
	v_sub_f32_e32 v116, v134, v135
	v_add_f32_e32 v126, v126, v127
.LBB0_552:
	s_or_b64 exec, exec, s[44:45]
	v_mov_b32_e32 v112, v117
	v_pk_mul_f32 v[132:133], v[112:113], v[130:131]
	s_and_saveexec_b64 s[44:45], s[2:3]
	s_xor_b64 s[44:45], exec, s[44:45]
	v_mov_b32_e32 v113, v133
	s_andn2_saveexec_b64 s[44:45], s[44:45]
	s_cbranch_execz .LBB0_556
	v_mov_b32_e32 v112, v246
	v_mov_b32_e32 v113, v247
	v_pk_mul_f32 v[134:135], v[132:133], v[112:113] op_sel:[1,0] op_sel_hi:[0,1]
	v_pk_mul_f32 v[112:113], v[132:133], v[112:113]
	s_nop 0
	v_add_f32_e32 v132, v112, v113
	v_sub_f32_e32 v113, v134, v135
.LBB0_556:
	s_or_b64 exec, exec, s[44:45]
	v_mov_b32_e32 v134, v118
	v_mov_b32_e32 v135, v114
	v_pk_mul_f32 v[134:135], v[134:135], v[130:131]
	s_and_saveexec_b64 s[44:45], s[2:3]
	s_xor_b64 s[44:45], exec, s[44:45]
	s_andn2_saveexec_b64 s[44:45], s[44:45]
	s_cbranch_execz .LBB0_558
	v_mov_b32_e32 v136, v248
	v_mov_b32_e32 v137, v249
	v_pk_mul_f32 v[148:149], v[134:135], v[136:137] op_sel:[1,0] op_sel_hi:[0,1]
	v_pk_mul_f32 v[134:135], v[134:135], v[136:137]
	s_nop 0
	v_add_f32_e32 v134, v134, v135
	v_sub_f32_e32 v135, v148, v149
; DEVI void phase2(const Params& p, char* shm) {
;     ...
;       auto ep = [&](Acc256& acc) {
;         EPI_IDX;
; #pragma unroll
;         for (int ai = 0; ai < 2; ++ai)
; #pragma unroll
;           for (int m = 0; m < 4; ++m) {
;             int rl = ai * 128 + wr * 64 + m * 16 + fr;
;             float rs = rsb[rl];
;             int row = brow + rl;
;             int pos = row & 4095;
; #pragma unroll
;             for (int bj = 0; bj < 2; ++bj) {
;               int cA = bcol + bj * 128 + wc * 32;
;               bool isrope = (cA % 96) == 64;
;               f32x4 va = acc[ai][bj][m][0], vb = acc[ai][bj][m][1];
;               float oa[4], ob[4];
; #pragma unroll
;               for (int j = 0; j < 4; ++j) {
;                 float x1 = va[j] * rs, x2 = vb[j] * rs;
;                 if (isrope) {
;                   float2 cs = tab[pos * 16 + fq * 4 + j];
;                   oa[j] = x1 * cs.x - x2 * cs.y;
;                   ob[j] = x1 * cs.y + x2 * cs.x;
;                 } else {
;                   oa[j] = x1;
;                   ob[j] = x2;
;                 }
;               }
;               uint2 pa, pb;
;               pa.x = pack2(oa[0], oa[1]); pa.y = pack2(oa[2], oa[3]);
;               pb.x = pack2(ob[0], ob[1]); pb.y = pack2(ob[2], ob[3]);
;               *reinterpret_cast<uint4*>(Qb + (size_t)row * 768 + cA + (fq & 1) * 16 + (fq >> 1) * 8) = widen_pair(pa, pb);
;             }
.LBB0_558:
	s_or_b64 exec, exec, s[44:45]
	v_mov_b32_e32 v114, v119
	v_pk_mul_f32 v[114:115], v[114:115], v[130:131]
	s_and_saveexec_b64 s[44:45], s[2:3]
	s_xor_b64 s[44:45], exec, s[44:45]
	s_andn2_saveexec_b64 s[44:45], s[44:45]
	s_cbranch_execz .LBB0_562
	v_mov_b32_e32 v118, v250
	v_mov_b32_e32 v119, v251
	v_pk_mul_f32 v[130:131], v[114:115], v[118:119] op_sel:[1,0] op_sel_hi:[0,1]
	v_pk_mul_f32 v[114:115], v[114:115], v[118:119]
	s_nop 0
	v_add_f32_e32 v114, v114, v115
	v_sub_f32_e32 v115, v130, v131
.LBB0_562:
	s_or_b64 exec, exec, s[44:45]
	v_cvt_pk_bf16_f32 v116, v116, v113
	v_or_b32_e32 v113, 16, v146
	v_lshl_add_u32 v112, v113, 2, 0
	v_add_u32_e32 v112, 0x20000, v112
	ds_read_b32 v112, v112
	v_cvt_pk_bf16_f32 v117, v135, v115
	v_cvt_pk_bf16_f32 v118, v126, v132
	v_cvt_pk_bf16_f32 v119, v134, v114
	v_mov_b32_e32 v114, v108
	v_mov_b32_e32 v115, v104
	v_permlane16_swap_b32_e32 v116, v118
	v_permlane16_swap_b32_e32 v117, v119
	s_waitcnt lgkmcnt(0)
	v_pk_mul_f32 v[114:115], v[114:115], v[112:113] op_sel_hi:[1,0]
	global_store_dwordx4 v[124:125], v[116:119], off offset:256
	s_and_saveexec_b64 s[44:45], vcc
	s_xor_b64 s[44:45], exec, s[44:45]
	v_mov_b32_e32 v108, v115
	s_or_saveexec_b64 s[44:45], s[44:45]
	v_add_u32_e32 v121, s79, v113
	v_lshlrev_b32_e32 v104, 4, v121
	s_mov_b32 s6, 0xfdf0
	v_and_or_b32 v104, v104, s6, v144
	v_lshlrev_b32_e32 v124, 3, v104
	global_load_dwordx2 v[244:245], v124, s[22:23]
	global_load_dwordx2 v[246:247], v124, s[22:23] offset:8
	global_load_dwordx2 v[248:249], v124, s[22:23] offset:16
	global_load_dwordx2 v[250:251], v124, s[22:23] offset:24
	s_waitcnt vmcnt(0)
	s_xor_b64 exec, exec, s[44:45]
	s_cbranch_execz .LBB0_566
	v_mov_b32_e32 v116, v244
	v_mov_b32_e32 v117, v245
	v_pk_mul_f32 v[118:119], v[114:115], v[116:117] op_sel:[1,0] op_sel_hi:[0,1]
	v_pk_mul_f32 v[114:115], v[114:115], v[116:117]
	v_sub_f32_e32 v108, v118, v119
	v_add_f32_e32 v114, v114, v115
.LBB0_566:
	s_or_b64 exec, exec, s[44:45]
	v_mov_b32_e32 v113, v112
	v_mov_b32_e32 v104, v109
	v_pk_mul_f32 v[116:117], v[104:105], v[112:113]
	s_and_saveexec_b64 s[44:45], vcc
	s_xor_b64 s[44:45], exec, s[44:45]
	v_mov_b32_e32 v105, v117
	s_andn2_saveexec_b64 s[44:45], s[44:45]
	s_cbranch_execz .LBB0_570
	v_mov_b32_e32 v104, v246
	v_mov_b32_e32 v105, v247
	v_pk_mul_f32 v[118:119], v[116:117], v[104:105] op_sel:[1,0] op_sel_hi:[0,1]
	v_pk_mul_f32 v[104:105], v[116:117], v[104:105]
	s_nop 0
	v_add_f32_e32 v116, v104, v105
	v_sub_f32_e32 v105, v118, v119
.LBB0_570:
	s_or_b64 exec, exec, s[44:45]
	v_mov_b32_e32 v118, v110
	v_mov_b32_e32 v119, v106
	v_pk_mul_f32 v[118:119], v[118:119], v[112:113]
	s_and_saveexec_b64 s[44:45], vcc
	s_xor_b64 s[44:45], exec, s[44:45]
	s_andn2_saveexec_b64 s[44:45], s[44:45]
	s_cbranch_execz .LBB0_572
	v_mov_b32_e32 v126, v248
	v_mov_b32_e32 v127, v249
	v_pk_mul_f32 v[130:131], v[118:119], v[126:127] op_sel:[1,0] op_sel_hi:[0,1]
	v_pk_mul_f32 v[118:119], v[118:119], v[126:127]
	s_nop 0
	v_add_f32_e32 v118, v118, v119
	v_sub_f32_e32 v119, v130, v131
.LBB0_572:
	s_or_b64 exec, exec, s[44:45]
	v_mov_b32_e32 v106, v111
	v_pk_mul_f32 v[106:107], v[106:107], v[112:113]
	s_and_saveexec_b64 s[44:45], vcc
	s_xor_b64 s[44:45], exec, s[44:45]
	s_andn2_saveexec_b64 s[44:45], s[44:45]
	s_cbranch_execz .LBB0_574
	v_mov_b32_e32 v110, v250
	v_mov_b32_e32 v111, v251
	v_pk_mul_f32 v[126:127], v[106:107], v[110:111] op_sel:[1,0] op_sel_hi:[0,1]
	v_pk_mul_f32 v[106:107], v[106:107], v[110:111]
	s_nop 0
	v_add_f32_e32 v106, v106, v107
	v_sub_f32_e32 v107, v126, v127
.LBB0_574:
	s_or_b64 exec, exec, s[44:45]
	v_cvt_pk_bf16_f32 v108, v108, v105
	v_mov_b64_e32 v[104:105], s[40:41]
	v_mad_i64_i32 v[104:105], s[44:45], v121, s59, v[104:105]
	v_lshl_add_u64 v[104:105], v[104:105], 0, v[128:129]
	v_mov_b32_e32 v121, v129
	v_cvt_pk_bf16_f32 v109, v119, v107
	v_cvt_pk_bf16_f32 v110, v114, v116
	v_cvt_pk_bf16_f32 v111, v118, v106
	v_lshl_add_u64 v[104:105], v[104:105], 0, v[120:121]
	v_mov_b32_e32 v123, v129
	v_mov_b32_e32 v106, v100
	v_mov_b32_e32 v107, v96
	v_permlane16_swap_b32_e32 v108, v110
	v_permlane16_swap_b32_e32 v109, v111
	v_lshl_add_u64 v[104:105], v[104:105], 0, v[122:123]
	v_pk_mul_f32 v[106:107], v[106:107], v[112:113]
	global_store_dwordx4 v[104:105], v[108:111], off
	s_and_saveexec_b64 s[44:45], s[2:3]
	s_xor_b64 s[44:45], exec, s[44:45]
	v_mov_b32_e32 v100, v107
	s_andn2_saveexec_b64 s[44:45], s[44:45]
	s_cbranch_execz .LBB0_578
	v_mov_b32_e32 v108, v244
	v_mov_b32_e32 v109, v245
	v_pk_mul_f32 v[110:111], v[106:107], v[108:109] op_sel:[1,0] op_sel_hi:[0,1]
	v_pk_mul_f32 v[106:107], v[106:107], v[108:109]
	v_sub_f32_e32 v100, v110, v111
	v_add_f32_e32 v106, v106, v107
.LBB0_578:
	s_or_b64 exec, exec, s[44:45]
	v_mov_b32_e32 v96, v101
	v_pk_mul_f32 v[108:109], v[96:97], v[112:113]
	s_and_saveexec_b64 s[44:45], s[2:3]
	s_xor_b64 s[44:45], exec, s[44:45]
	v_mov_b32_e32 v97, v109
	s_andn2_saveexec_b64 s[44:45], s[44:45]
	s_cbranch_execz .LBB0_582
	v_mov_b32_e32 v96, v246
	v_mov_b32_e32 v97, v247
	v_pk_mul_f32 v[110:111], v[108:109], v[96:97] op_sel:[1,0] op_sel_hi:[0,1]
	v_pk_mul_f32 v[96:97], v[108:109], v[96:97]
	s_nop 0
	v_add_f32_e32 v108, v96, v97
	v_sub_f32_e32 v97, v110, v111
.LBB0_582:
	s_or_b64 exec, exec, s[44:45]
	v_mov_b32_e32 v110, v102
	v_mov_b32_e32 v111, v98
	v_pk_mul_f32 v[110:111], v[110:111], v[112:113]
	s_and_saveexec_b64 s[44:45], s[2:3]
	s_xor_b64 s[44:45], exec, s[44:45]
	s_andn2_saveexec_b64 s[44:45], s[44:45]
	s_cbranch_execz .LBB0_584
	v_mov_b32_e32 v114, v248
	v_mov_b32_e32 v115, v249
	v_pk_mul_f32 v[116:117], v[110:111], v[114:115] op_sel:[1,0] op_sel_hi:[0,1]
	v_pk_mul_f32 v[110:111], v[110:111], v[114:115]
	s_nop 0
	v_add_f32_e32 v110, v110, v111
	v_sub_f32_e32 v111, v116, v117
; DEVI void phase2(const Params& p, char* shm) {
;     ...
;       auto ep = [&](Acc256& acc) {
;         EPI_IDX;
; #pragma unroll
;         for (int ai = 0; ai < 2; ++ai)
; #pragma unroll
;           for (int m = 0; m < 4; ++m) {
;             int rl = ai * 128 + wr * 64 + m * 16 + fr;
;             float rs = rsb[rl];
;             int row = brow + rl;
;             int pos = row & 4095;
; #pragma unroll
;             for (int bj = 0; bj < 2; ++bj) {
;               int cA = bcol + bj * 128 + wc * 32;
;               bool isrope = (cA % 96) == 64;
;               f32x4 va = acc[ai][bj][m][0], vb = acc[ai][bj][m][1];
;               float oa[4], ob[4];
; #pragma unroll
;               for (int j = 0; j < 4; ++j) {
;                 float x1 = va[j] * rs, x2 = vb[j] * rs;
;                 if (isrope) {
;                   float2 cs = tab[pos * 16 + fq * 4 + j];
;                   oa[j] = x1 * cs.x - x2 * cs.y;
;                   ob[j] = x1 * cs.y + x2 * cs.x;
;                 } else {
;                   oa[j] = x1;
;                   ob[j] = x2;
;                 }
;               }
;               uint2 pa, pb;
;               pa.x = pack2(oa[0], oa[1]); pa.y = pack2(oa[2], oa[3]);
;               pb.x = pack2(ob[0], ob[1]); pb.y = pack2(ob[2], ob[3]);
;               *reinterpret_cast<uint4*>(Qb + (size_t)row * 768 + cA + (fq & 1) * 16 + (fq >> 1) * 8) = widen_pair(pa, pb);
;             }
.LBB0_584:
	s_or_b64 exec, exec, s[44:45]
	v_mov_b32_e32 v98, v103
	v_pk_mul_f32 v[98:99], v[98:99], v[112:113]
	s_and_saveexec_b64 s[44:45], s[2:3]
	s_xor_b64 s[44:45], exec, s[44:45]
	s_andn2_saveexec_b64 s[44:45], s[44:45]
	s_cbranch_execz .LBB0_588
	v_mov_b32_e32 v102, v250
	v_mov_b32_e32 v103, v251
	v_pk_mul_f32 v[112:113], v[98:99], v[102:103] op_sel:[1,0] op_sel_hi:[0,1]
	v_pk_mul_f32 v[98:99], v[98:99], v[102:103]
	s_nop 0
	v_add_f32_e32 v98, v98, v99
	v_sub_f32_e32 v99, v112, v113
.LBB0_588:
	s_or_b64 exec, exec, s[44:45]
	v_cvt_pk_bf16_f32 v100, v100, v97
	v_or_b32_e32 v97, 32, v146
	v_lshl_add_u32 v96, v97, 2, 0
	v_add_u32_e32 v96, 0x20000, v96
	ds_read_b32 v96, v96
	v_cvt_pk_bf16_f32 v101, v111, v99
	v_cvt_pk_bf16_f32 v102, v106, v108
	v_cvt_pk_bf16_f32 v103, v110, v98
	v_mov_b32_e32 v98, v92
	v_mov_b32_e32 v99, v88
	v_permlane16_swap_b32_e32 v100, v102
	v_permlane16_swap_b32_e32 v101, v103
	s_waitcnt lgkmcnt(0)
	v_pk_mul_f32 v[98:99], v[98:99], v[96:97] op_sel_hi:[1,0]
	global_store_dwordx4 v[104:105], v[100:103], off offset:256
	s_and_saveexec_b64 s[44:45], vcc
	s_xor_b64 s[44:45], exec, s[44:45]
	v_mov_b32_e32 v92, v99
	s_or_saveexec_b64 s[44:45], s[44:45]
	v_add_u32_e32 v105, s79, v97
	v_lshlrev_b32_e32 v88, 4, v105
	s_mov_b32 s6, 0xfef0
	v_and_or_b32 v88, v88, s6, v144
	v_lshlrev_b32_e32 v104, 3, v88
	global_load_dwordx2 v[244:245], v104, s[22:23]
	global_load_dwordx2 v[246:247], v104, s[22:23] offset:8
	global_load_dwordx2 v[248:249], v104, s[22:23] offset:16
	global_load_dwordx2 v[250:251], v104, s[22:23] offset:24
	s_waitcnt vmcnt(0)
	s_xor_b64 exec, exec, s[44:45]
	s_cbranch_execz .LBB0_592
	v_mov_b32_e32 v100, v244
	v_mov_b32_e32 v101, v245
	v_pk_mul_f32 v[102:103], v[98:99], v[100:101] op_sel:[1,0] op_sel_hi:[0,1]
	v_pk_mul_f32 v[98:99], v[98:99], v[100:101]
	v_sub_f32_e32 v92, v102, v103
	v_add_f32_e32 v98, v98, v99
.LBB0_592:
	s_or_b64 exec, exec, s[44:45]
	v_mov_b32_e32 v97, v96
	v_mov_b32_e32 v88, v93
	v_pk_mul_f32 v[100:101], v[88:89], v[96:97]
	s_and_saveexec_b64 s[44:45], vcc
	s_xor_b64 s[44:45], exec, s[44:45]
	v_mov_b32_e32 v89, v101
	s_andn2_saveexec_b64 s[44:45], s[44:45]
	s_cbranch_execz .LBB0_596
	v_mov_b32_e32 v88, v246
	v_mov_b32_e32 v89, v247
	v_pk_mul_f32 v[102:103], v[100:101], v[88:89] op_sel:[1,0] op_sel_hi:[0,1]
	v_pk_mul_f32 v[88:89], v[100:101], v[88:89]
	s_nop 0
	v_add_f32_e32 v100, v88, v89
	v_sub_f32_e32 v89, v102, v103
.LBB0_596:
	s_or_b64 exec, exec, s[44:45]
	v_mov_b32_e32 v102, v94
	v_mov_b32_e32 v103, v90
	v_pk_mul_f32 v[102:103], v[102:103], v[96:97]
	s_and_saveexec_b64 s[44:45], vcc
	s_xor_b64 s[44:45], exec, s[44:45]
	s_andn2_saveexec_b64 s[44:45], s[44:45]
	s_cbranch_execz .LBB0_598
	v_mov_b32_e32 v106, v248
	v_mov_b32_e32 v107, v249
	v_pk_mul_f32 v[108:109], v[102:103], v[106:107] op_sel:[1,0] op_sel_hi:[0,1]
	v_pk_mul_f32 v[102:103], v[102:103], v[106:107]
	s_nop 0
	v_add_f32_e32 v102, v102, v103
	v_sub_f32_e32 v103, v108, v109
.LBB0_598:
	s_or_b64 exec, exec, s[44:45]
	v_mov_b32_e32 v90, v95
	v_pk_mul_f32 v[90:91], v[90:91], v[96:97]
	s_and_saveexec_b64 s[44:45], vcc
	s_xor_b64 s[44:45], exec, s[44:45]
	s_andn2_saveexec_b64 s[44:45], s[44:45]
	s_cbranch_execz .LBB0_600
	v_mov_b32_e32 v94, v250
	v_mov_b32_e32 v95, v251
	v_pk_mul_f32 v[106:107], v[90:91], v[94:95] op_sel:[1,0] op_sel_hi:[0,1]
	v_pk_mul_f32 v[90:91], v[90:91], v[94:95]
	s_nop 0
	v_add_f32_e32 v90, v90, v91
	v_sub_f32_e32 v91, v106, v107
.LBB0_600:
	s_or_b64 exec, exec, s[44:45]
	v_cvt_pk_bf16_f32 v92, v92, v89
	v_mov_b64_e32 v[88:89], s[40:41]
	v_mad_i64_i32 v[88:89], s[44:45], v105, s59, v[88:89]
	v_lshl_add_u64 v[88:89], v[88:89], 0, v[128:129]
	v_mov_b32_e32 v121, v129
	v_cvt_pk_bf16_f32 v93, v103, v91
	v_cvt_pk_bf16_f32 v94, v98, v100
	v_cvt_pk_bf16_f32 v95, v102, v90
	v_lshl_add_u64 v[88:89], v[88:89], 0, v[120:121]
	v_mov_b32_e32 v123, v129
	v_mov_b32_e32 v90, v84
	v_mov_b32_e32 v91, v80
	v_permlane16_swap_b32_e32 v92, v94
	v_permlane16_swap_b32_e32 v93, v95
	v_lshl_add_u64 v[88:89], v[88:89], 0, v[122:123]
	v_pk_mul_f32 v[90:91], v[90:91], v[96:97]
	global_store_dwordx4 v[88:89], v[92:95], off
	s_and_saveexec_b64 s[44:45], s[2:3]
	s_xor_b64 s[44:45], exec, s[44:45]
	v_mov_b32_e32 v84, v91
	s_andn2_saveexec_b64 s[44:45], s[44:45]
	s_cbranch_execz .LBB0_604
	v_mov_b32_e32 v92, v244
	v_mov_b32_e32 v93, v245
	v_pk_mul_f32 v[94:95], v[90:91], v[92:93] op_sel:[1,0] op_sel_hi:[0,1]
	v_pk_mul_f32 v[90:91], v[90:91], v[92:93]
	v_sub_f32_e32 v84, v94, v95
	v_add_f32_e32 v90, v90, v91
.LBB0_604:
	s_or_b64 exec, exec, s[44:45]
	v_mov_b32_e32 v80, v85
	v_pk_mul_f32 v[92:93], v[80:81], v[96:97]
	s_and_saveexec_b64 s[44:45], s[2:3]
	s_xor_b64 s[44:45], exec, s[44:45]
	v_mov_b32_e32 v81, v93
	s_andn2_saveexec_b64 s[44:45], s[44:45]
	s_cbranch_execz .LBB0_608
	v_mov_b32_e32 v80, v246
	v_mov_b32_e32 v81, v247
	v_pk_mul_f32 v[94:95], v[92:93], v[80:81] op_sel:[1,0] op_sel_hi:[0,1]
	v_pk_mul_f32 v[80:81], v[92:93], v[80:81]
	s_nop 0
	v_add_f32_e32 v92, v80, v81
	v_sub_f32_e32 v81, v94, v95
.LBB0_608:
	s_or_b64 exec, exec, s[44:45]
	v_mov_b32_e32 v94, v86
	v_mov_b32_e32 v95, v82
	v_pk_mul_f32 v[94:95], v[94:95], v[96:97]
	s_and_saveexec_b64 s[44:45], s[2:3]
	s_xor_b64 s[44:45], exec, s[44:45]
	s_andn2_saveexec_b64 s[44:45], s[44:45]
	s_cbranch_execz .LBB0_610
	v_mov_b32_e32 v98, v248
	v_mov_b32_e32 v99, v249
	v_pk_mul_f32 v[100:101], v[94:95], v[98:99] op_sel:[1,0] op_sel_hi:[0,1]
	v_pk_mul_f32 v[94:95], v[94:95], v[98:99]
	s_nop 0
	v_add_f32_e32 v94, v94, v95
	v_sub_f32_e32 v95, v100, v101
; DEVI void phase2(const Params& p, char* shm) {
;     ...
;       auto ep = [&](Acc256& acc) {
;         EPI_IDX;
; #pragma unroll
;         for (int ai = 0; ai < 2; ++ai)
; #pragma unroll
;           for (int m = 0; m < 4; ++m) {
;             int rl = ai * 128 + wr * 64 + m * 16 + fr;
;             float rs = rsb[rl];
;             int row = brow + rl;
;             int pos = row & 4095;
; #pragma unroll
;             for (int bj = 0; bj < 2; ++bj) {
;               int cA = bcol + bj * 128 + wc * 32;
;               bool isrope = (cA % 96) == 64;
;               f32x4 va = acc[ai][bj][m][0], vb = acc[ai][bj][m][1];
;               float oa[4], ob[4];
; #pragma unroll
;               for (int j = 0; j < 4; ++j) {
;                 float x1 = va[j] * rs, x2 = vb[j] * rs;
;                 if (isrope) {
;                   float2 cs = tab[pos * 16 + fq * 4 + j];
;                   oa[j] = x1 * cs.x - x2 * cs.y;
;                   ob[j] = x1 * cs.y + x2 * cs.x;
;                 } else {
;                   oa[j] = x1;
;                   ob[j] = x2;
;                 }
;               }
;               uint2 pa, pb;
;               pa.x = pack2(oa[0], oa[1]); pa.y = pack2(oa[2], oa[3]);
;               pb.x = pack2(ob[0], ob[1]); pb.y = pack2(ob[2], ob[3]);
;               *reinterpret_cast<uint4*>(Qb + (size_t)row * 768 + cA + (fq & 1) * 16 + (fq >> 1) * 8) = widen_pair(pa, pb);
;             }
.LBB0_610:
	s_or_b64 exec, exec, s[44:45]
	v_mov_b32_e32 v82, v87
	v_pk_mul_f32 v[82:83], v[82:83], v[96:97]
	s_and_saveexec_b64 s[44:45], s[2:3]
	s_xor_b64 s[44:45], exec, s[44:45]
	s_andn2_saveexec_b64 s[44:45], s[44:45]
	s_cbranch_execz .LBB0_614
	v_mov_b32_e32 v86, v250
	v_mov_b32_e32 v87, v251
	v_pk_mul_f32 v[96:97], v[82:83], v[86:87] op_sel:[1,0] op_sel_hi:[0,1]
	v_pk_mul_f32 v[82:83], v[82:83], v[86:87]
	s_nop 0
	v_add_f32_e32 v82, v82, v83
	v_sub_f32_e32 v83, v96, v97
.LBB0_614:
	s_or_b64 exec, exec, s[44:45]
	v_cvt_pk_bf16_f32 v84, v84, v81
	v_or_b32_e32 v81, 48, v146
	v_lshl_add_u32 v80, v81, 2, 0
	v_add_u32_e32 v80, 0x20000, v80
	ds_read_b32 v80, v80
	v_cvt_pk_bf16_f32 v85, v95, v83
	v_cvt_pk_bf16_f32 v86, v90, v92
	v_cvt_pk_bf16_f32 v87, v94, v82
	v_mov_b32_e32 v82, v76
	v_mov_b32_e32 v83, v72
	v_permlane16_swap_b32_e32 v84, v86
	v_permlane16_swap_b32_e32 v85, v87
	s_waitcnt lgkmcnt(0)
	v_pk_mul_f32 v[82:83], v[82:83], v[80:81] op_sel_hi:[1,0]
	global_store_dwordx4 v[88:89], v[84:87], off offset:256
	s_and_saveexec_b64 s[44:45], vcc
	s_xor_b64 s[44:45], exec, s[44:45]
	v_mov_b32_e32 v76, v83
	s_or_saveexec_b64 s[44:45], s[44:45]
	v_add_u32_e32 v89, s79, v81
	v_lshlrev_b32_e32 v72, 4, v89
	v_and_or_b32 v72, v72, s71, v144
	v_lshlrev_b32_e32 v88, 3, v72
	global_load_dwordx2 v[244:245], v88, s[22:23]
	global_load_dwordx2 v[246:247], v88, s[22:23] offset:8
	global_load_dwordx2 v[248:249], v88, s[22:23] offset:16
	global_load_dwordx2 v[250:251], v88, s[22:23] offset:24
	s_waitcnt vmcnt(0)
	s_xor_b64 exec, exec, s[44:45]
	s_cbranch_execz .LBB0_618
	v_mov_b32_e32 v84, v244
	v_mov_b32_e32 v85, v245
	v_pk_mul_f32 v[86:87], v[82:83], v[84:85] op_sel:[1,0] op_sel_hi:[0,1]
	v_pk_mul_f32 v[82:83], v[82:83], v[84:85]
	v_sub_f32_e32 v76, v86, v87
	v_add_f32_e32 v82, v82, v83
.LBB0_618:
	s_or_b64 exec, exec, s[44:45]
	v_mov_b32_e32 v81, v80
	v_mov_b32_e32 v72, v77
	v_pk_mul_f32 v[84:85], v[72:73], v[80:81]
	s_and_saveexec_b64 s[44:45], vcc
	s_xor_b64 s[44:45], exec, s[44:45]
	v_mov_b32_e32 v73, v85
	s_andn2_saveexec_b64 s[44:45], s[44:45]
	s_cbranch_execz .LBB0_622
	v_mov_b32_e32 v72, v246
	v_mov_b32_e32 v73, v247
	v_pk_mul_f32 v[86:87], v[84:85], v[72:73] op_sel:[1,0] op_sel_hi:[0,1]
	v_pk_mul_f32 v[72:73], v[84:85], v[72:73]
	s_nop 0
	v_add_f32_e32 v84, v72, v73
	v_sub_f32_e32 v73, v86, v87
.LBB0_622:
	s_or_b64 exec, exec, s[44:45]
	v_mov_b32_e32 v86, v78
	v_mov_b32_e32 v87, v74
	v_pk_mul_f32 v[86:87], v[86:87], v[80:81]
	s_and_saveexec_b64 s[44:45], vcc
	s_xor_b64 s[44:45], exec, s[44:45]
	s_andn2_saveexec_b64 s[44:45], s[44:45]
	s_cbranch_execz .LBB0_624
	v_mov_b32_e32 v90, v248
	v_mov_b32_e32 v91, v249
	v_pk_mul_f32 v[92:93], v[86:87], v[90:91] op_sel:[1,0] op_sel_hi:[0,1]
	v_pk_mul_f32 v[86:87], v[86:87], v[90:91]
	s_nop 0
	v_add_f32_e32 v86, v86, v87
	v_sub_f32_e32 v87, v92, v93
.LBB0_624:
	s_or_b64 exec, exec, s[44:45]
	v_mov_b32_e32 v74, v79
	v_pk_mul_f32 v[74:75], v[74:75], v[80:81]
	s_and_saveexec_b64 s[44:45], vcc
	s_xor_b64 s[44:45], exec, s[44:45]
	s_andn2_saveexec_b64 s[44:45], s[44:45]
	s_cbranch_execz .LBB0_626
	v_mov_b32_e32 v78, v250
	v_mov_b32_e32 v79, v251
	v_pk_mul_f32 v[90:91], v[74:75], v[78:79] op_sel:[1,0] op_sel_hi:[0,1]
	v_pk_mul_f32 v[74:75], v[74:75], v[78:79]
	s_nop 0
	v_add_f32_e32 v74, v74, v75
	v_sub_f32_e32 v75, v90, v91
.LBB0_626:
	s_or_b64 exec, exec, s[44:45]
	v_cvt_pk_bf16_f32 v76, v76, v73
	v_mov_b64_e32 v[72:73], s[40:41]
	v_mad_i64_i32 v[72:73], s[44:45], v89, s59, v[72:73]
	v_lshl_add_u64 v[72:73], v[72:73], 0, v[128:129]
	v_mov_b32_e32 v121, v129
	v_cvt_pk_bf16_f32 v77, v87, v75
	v_cvt_pk_bf16_f32 v78, v82, v84
	v_cvt_pk_bf16_f32 v79, v86, v74
	v_lshl_add_u64 v[72:73], v[72:73], 0, v[120:121]
	v_mov_b32_e32 v123, v129
	v_mov_b32_e32 v74, v68
	v_mov_b32_e32 v75, v64
	v_permlane16_swap_b32_e32 v76, v78
	v_permlane16_swap_b32_e32 v77, v79
	v_lshl_add_u64 v[72:73], v[72:73], 0, v[122:123]
	v_pk_mul_f32 v[74:75], v[74:75], v[80:81]
	global_store_dwordx4 v[72:73], v[76:79], off
	s_and_saveexec_b64 s[44:45], s[2:3]
	s_xor_b64 s[44:45], exec, s[44:45]
	v_mov_b32_e32 v68, v75
	s_andn2_saveexec_b64 s[44:45], s[44:45]
	s_cbranch_execz .LBB0_630
	v_mov_b32_e32 v76, v244
	v_mov_b32_e32 v77, v245
	v_pk_mul_f32 v[78:79], v[74:75], v[76:77] op_sel:[1,0] op_sel_hi:[0,1]
	v_pk_mul_f32 v[74:75], v[74:75], v[76:77]
	v_sub_f32_e32 v68, v78, v79
	v_add_f32_e32 v74, v74, v75
.LBB0_630:
	s_or_b64 exec, exec, s[44:45]
	v_mov_b32_e32 v64, v69
	v_pk_mul_f32 v[76:77], v[64:65], v[80:81]
	s_and_saveexec_b64 s[44:45], s[2:3]
	s_xor_b64 s[44:45], exec, s[44:45]
	v_mov_b32_e32 v65, v77
	s_andn2_saveexec_b64 s[44:45], s[44:45]
	s_cbranch_execz .LBB0_634
	v_mov_b32_e32 v64, v246
	v_mov_b32_e32 v65, v247
	v_pk_mul_f32 v[78:79], v[76:77], v[64:65] op_sel:[1,0] op_sel_hi:[0,1]
	v_pk_mul_f32 v[64:65], v[76:77], v[64:65]
	s_nop 0
	v_add_f32_e32 v76, v64, v65
	v_sub_f32_e32 v65, v78, v79
.LBB0_634:
	s_or_b64 exec, exec, s[44:45]
	v_mov_b32_e32 v78, v70
	v_mov_b32_e32 v79, v66
	v_pk_mul_f32 v[78:79], v[78:79], v[80:81]
	s_and_saveexec_b64 s[44:45], s[2:3]
	s_xor_b64 s[44:45], exec, s[44:45]
	s_andn2_saveexec_b64 s[44:45], s[44:45]
	s_cbranch_execz .LBB0_636
	v_mov_b32_e32 v82, v248
	v_mov_b32_e32 v83, v249
	v_pk_mul_f32 v[84:85], v[78:79], v[82:83] op_sel:[1,0] op_sel_hi:[0,1]
	v_pk_mul_f32 v[78:79], v[78:79], v[82:83]
	s_nop 0
	v_add_f32_e32 v78, v78, v79
	v_sub_f32_e32 v79, v84, v85
.LBB0_636:
	s_or_b64 exec, exec, s[44:45]
	v_mov_b32_e32 v66, v71
	v_pk_mul_f32 v[66:67], v[66:67], v[80:81]
	s_and_saveexec_b64 s[44:45], s[2:3]
	s_xor_b64 s[44:45], exec, s[44:45]
	s_andn2_saveexec_b64 s[44:45], s[44:45]
	s_cbranch_execz .LBB0_640
	v_mov_b32_e32 v70, v250
	v_mov_b32_e32 v71, v251
	v_pk_mul_f32 v[80:81], v[66:67], v[70:71] op_sel:[1,0] op_sel_hi:[0,1]
	v_pk_mul_f32 v[66:67], v[66:67], v[70:71]
	s_nop 0
	v_add_f32_e32 v66, v66, v67
	v_sub_f32_e32 v67, v80, v81
; DEVI void phase2(const Params& p, char* shm) {
;     ...
;           for (int m = 0; m < 4; ++m) {
;             int rl = ai * 128 + wr * 64 + m * 16 + fr;
;             float rs = rsb[rl];
;             int row = brow + rl;
;             int pos = row & 4095;
; #pragma unroll
;             for (int bj = 0; bj < 2; ++bj) {
;               int cA = bcol + bj * 128 + wc * 32;
;               bool isrope = (cA % 96) == 64;
;               f32x4 va = acc[ai][bj][m][0], vb = acc[ai][bj][m][1];
;               float oa[4], ob[4];
; #pragma unroll
;               for (int j = 0; j < 4; ++j) {
;                 float x1 = va[j] * rs, x2 = vb[j] * rs;
;                 if (isrope) {
;                   float2 cs = tab[pos * 16 + fq * 4 + j];
;                   oa[j] = x1 * cs.x - x2 * cs.y;
;                   ob[j] = x1 * cs.y + x2 * cs.x;
;                 } else {
;                   oa[j] = x1;
;                   ob[j] = x2;
;                 }
;               }
;               uint2 pa, pb;
;               pa.x = pack2(oa[0], oa[1]); pa.y = pack2(oa[2], oa[3]);
;               pb.x = pack2(ob[0], ob[1]); pb.y = pack2(ob[2], ob[3]);
;               *reinterpret_cast<uint4*>(Qb + (size_t)row * 768 + cA + (fq & 1) * 16 + (fq >> 1) * 8) = widen_pair(pa, pb);
.LBB0_640:
	s_or_b64 exec, exec, s[44:45]
	ds_read_b32 v64, v143 offset:512
	v_cvt_pk_bf16_f32 v68, v68, v65
	v_cvt_pk_bf16_f32 v69, v79, v67
	v_cvt_pk_bf16_f32 v70, v74, v76
	v_cvt_pk_bf16_f32 v71, v78, v66
	v_mov_b32_e32 v66, v60
	v_mov_b32_e32 v67, v56
	v_permlane16_swap_b32_e32 v68, v70
	v_permlane16_swap_b32_e32 v69, v71
	s_waitcnt lgkmcnt(0)
	v_pk_mul_f32 v[66:67], v[66:67], v[64:65] op_sel_hi:[1,0]
	global_store_dwordx4 v[72:73], v[68:71], off offset:256
	s_and_saveexec_b64 s[44:45], vcc
	s_xor_b64 s[44:45], exec, s[44:45]
	v_mov_b32_e32 v60, v67
	s_or_saveexec_b64 s[44:45], s[44:45]
	v_add_u32_e32 v73, 0x80, v145
	v_lshlrev_b32_e32 v56, 4, v73
	s_mov_b32 s6, 0xfcf0
	v_and_or_b32 v56, v56, s6, v144
	v_lshlrev_b32_e32 v72, 3, v56
	global_load_dwordx2 v[244:245], v72, s[22:23]
	global_load_dwordx2 v[246:247], v72, s[22:23] offset:8
	global_load_dwordx2 v[248:249], v72, s[22:23] offset:16
	global_load_dwordx2 v[250:251], v72, s[22:23] offset:24
	s_waitcnt vmcnt(0)
	s_xor_b64 exec, exec, s[44:45]
	s_cbranch_execz .LBB0_644
	v_mov_b32_e32 v68, v244
	v_mov_b32_e32 v69, v245
	v_pk_mul_f32 v[70:71], v[66:67], v[68:69] op_sel:[1,0] op_sel_hi:[0,1]
	v_pk_mul_f32 v[66:67], v[66:67], v[68:69]
	v_sub_f32_e32 v60, v70, v71
	v_add_f32_e32 v66, v66, v67
.LBB0_644:
	s_or_b64 exec, exec, s[44:45]
	v_mov_b32_e32 v65, v64
	v_mov_b32_e32 v56, v61
	v_pk_mul_f32 v[68:69], v[56:57], v[64:65]
	s_and_saveexec_b64 s[44:45], vcc
	s_xor_b64 s[44:45], exec, s[44:45]
	v_mov_b32_e32 v57, v69
	s_andn2_saveexec_b64 s[44:45], s[44:45]
	s_cbranch_execz .LBB0_648
	v_mov_b32_e32 v56, v246
	v_mov_b32_e32 v57, v247
	v_pk_mul_f32 v[70:71], v[68:69], v[56:57] op_sel:[1,0] op_sel_hi:[0,1]
	v_pk_mul_f32 v[56:57], v[68:69], v[56:57]
	s_nop 0
	v_add_f32_e32 v68, v56, v57
	v_sub_f32_e32 v57, v70, v71
.LBB0_648:
	s_or_b64 exec, exec, s[44:45]
	v_mov_b32_e32 v70, v62
	v_mov_b32_e32 v71, v58
	v_pk_mul_f32 v[70:71], v[70:71], v[64:65]
	s_and_saveexec_b64 s[44:45], vcc
	s_xor_b64 s[44:45], exec, s[44:45]
	s_andn2_saveexec_b64 s[44:45], s[44:45]
	s_cbranch_execz .LBB0_650
	v_mov_b32_e32 v74, v248
	v_mov_b32_e32 v75, v249
	v_pk_mul_f32 v[76:77], v[70:71], v[74:75] op_sel:[1,0] op_sel_hi:[0,1]
	v_pk_mul_f32 v[70:71], v[70:71], v[74:75]
	s_nop 0
	v_add_f32_e32 v70, v70, v71
	v_sub_f32_e32 v71, v76, v77
.LBB0_650:
	s_or_b64 exec, exec, s[44:45]
	v_mov_b32_e32 v58, v63
	v_pk_mul_f32 v[58:59], v[58:59], v[64:65]
	s_and_saveexec_b64 s[44:45], vcc
	s_xor_b64 s[44:45], exec, s[44:45]
	s_andn2_saveexec_b64 s[44:45], s[44:45]
	s_cbranch_execz .LBB0_652
	v_mov_b32_e32 v62, v250
	v_mov_b32_e32 v63, v251
	v_pk_mul_f32 v[74:75], v[58:59], v[62:63] op_sel:[1,0] op_sel_hi:[0,1]
	v_pk_mul_f32 v[58:59], v[58:59], v[62:63]
	s_nop 0
	v_add_f32_e32 v58, v58, v59
	v_sub_f32_e32 v59, v74, v75
.LBB0_652:
	s_or_b64 exec, exec, s[44:45]
	v_cvt_pk_bf16_f32 v60, v60, v57
	v_mov_b64_e32 v[56:57], s[40:41]
	v_mad_i64_i32 v[56:57], s[44:45], v73, s59, v[56:57]
	v_lshl_add_u64 v[56:57], v[56:57], 0, v[128:129]
	v_mov_b32_e32 v121, v129
	v_cvt_pk_bf16_f32 v61, v71, v59
	v_cvt_pk_bf16_f32 v62, v66, v68
	v_cvt_pk_bf16_f32 v63, v70, v58
	v_lshl_add_u64 v[56:57], v[56:57], 0, v[120:121]
	v_mov_b32_e32 v123, v129
	v_mov_b32_e32 v58, v52
	v_mov_b32_e32 v59, v48
	v_permlane16_swap_b32_e32 v60, v62
	v_permlane16_swap_b32_e32 v61, v63
	v_lshl_add_u64 v[56:57], v[56:57], 0, v[122:123]
	v_pk_mul_f32 v[58:59], v[58:59], v[64:65]
	global_store_dwordx4 v[56:57], v[60:63], off
	s_and_saveexec_b64 s[44:45], s[2:3]
	s_xor_b64 s[44:45], exec, s[44:45]
	v_mov_b32_e32 v52, v59
	s_andn2_saveexec_b64 s[44:45], s[44:45]
	s_cbranch_execz .LBB0_656
	v_mov_b32_e32 v60, v244
	v_mov_b32_e32 v61, v245
	v_pk_mul_f32 v[62:63], v[58:59], v[60:61] op_sel:[1,0] op_sel_hi:[0,1]
	v_pk_mul_f32 v[58:59], v[58:59], v[60:61]
	v_sub_f32_e32 v52, v62, v63
	v_add_f32_e32 v58, v58, v59
.LBB0_656:
	s_or_b64 exec, exec, s[44:45]
	v_mov_b32_e32 v48, v53
	v_pk_mul_f32 v[60:61], v[48:49], v[64:65]
	s_and_saveexec_b64 s[44:45], s[2:3]
	s_xor_b64 s[44:45], exec, s[44:45]
	v_mov_b32_e32 v49, v61
	s_andn2_saveexec_b64 s[44:45], s[44:45]
	s_cbranch_execz .LBB0_660
	v_mov_b32_e32 v48, v246
	v_mov_b32_e32 v49, v247
	v_pk_mul_f32 v[62:63], v[60:61], v[48:49] op_sel:[1,0] op_sel_hi:[0,1]
	v_pk_mul_f32 v[48:49], v[60:61], v[48:49]
	s_nop 0
	v_add_f32_e32 v60, v48, v49
	v_sub_f32_e32 v49, v62, v63
.LBB0_660:
	s_or_b64 exec, exec, s[44:45]
	v_mov_b32_e32 v62, v54
	v_mov_b32_e32 v63, v50
	v_pk_mul_f32 v[62:63], v[62:63], v[64:65]
	s_and_saveexec_b64 s[44:45], s[2:3]
	s_xor_b64 s[44:45], exec, s[44:45]
	s_andn2_saveexec_b64 s[44:45], s[44:45]
	s_cbranch_execz .LBB0_662
	v_mov_b32_e32 v66, v248
	v_mov_b32_e32 v67, v249
	v_pk_mul_f32 v[68:69], v[62:63], v[66:67] op_sel:[1,0] op_sel_hi:[0,1]
	v_pk_mul_f32 v[62:63], v[62:63], v[66:67]
	s_nop 0
	v_add_f32_e32 v62, v62, v63
	v_sub_f32_e32 v63, v68, v69
.LBB0_662:
	s_or_b64 exec, exec, s[44:45]
	v_mov_b32_e32 v50, v55
	v_pk_mul_f32 v[50:51], v[50:51], v[64:65]
	s_and_saveexec_b64 s[44:45], s[2:3]
	s_xor_b64 s[44:45], exec, s[44:45]
	s_andn2_saveexec_b64 s[44:45], s[44:45]
	s_cbranch_execz .LBB0_666
	v_mov_b32_e32 v54, v250
	v_mov_b32_e32 v55, v251
	v_pk_mul_f32 v[64:65], v[50:51], v[54:55] op_sel:[1,0] op_sel_hi:[0,1]
	v_pk_mul_f32 v[50:51], v[50:51], v[54:55]
	s_nop 0
	v_add_f32_e32 v50, v50, v51
	v_sub_f32_e32 v51, v64, v65
; DEVI void phase2(const Params& p, char* shm) {
;     ...
;           for (int m = 0; m < 4; ++m) {
;             int rl = ai * 128 + wr * 64 + m * 16 + fr;
;             float rs = rsb[rl];
;             int row = brow + rl;
;             int pos = row & 4095;
; #pragma unroll
;             for (int bj = 0; bj < 2; ++bj) {
;               int cA = bcol + bj * 128 + wc * 32;
;               bool isrope = (cA % 96) == 64;
;               f32x4 va = acc[ai][bj][m][0], vb = acc[ai][bj][m][1];
;               float oa[4], ob[4];
; #pragma unroll
;               for (int j = 0; j < 4; ++j) {
;                 float x1 = va[j] * rs, x2 = vb[j] * rs;
;                 if (isrope) {
;                   float2 cs = tab[pos * 16 + fq * 4 + j];
;                   oa[j] = x1 * cs.x - x2 * cs.y;
;                   ob[j] = x1 * cs.y + x2 * cs.x;
;                 } else {
;                   oa[j] = x1;
;                   ob[j] = x2;
;                 }
;               }
;               uint2 pa, pb;
;               pa.x = pack2(oa[0], oa[1]); pa.y = pack2(oa[2], oa[3]);
;               pb.x = pack2(ob[0], ob[1]); pb.y = pack2(ob[2], ob[3]);
;               *reinterpret_cast<uint4*>(Qb + (size_t)row * 768 + cA + (fq & 1) * 16 + (fq >> 1) * 8) = widen_pair(pa, pb);
.LBB0_666:
	s_or_b64 exec, exec, s[44:45]
	ds_read_b32 v48, v143 offset:576
	v_cvt_pk_bf16_f32 v52, v52, v49
	v_cvt_pk_bf16_f32 v53, v63, v51
	v_cvt_pk_bf16_f32 v54, v58, v60
	v_cvt_pk_bf16_f32 v55, v62, v50
	v_mov_b32_e32 v50, v44
	v_mov_b32_e32 v51, v40
	v_permlane16_swap_b32_e32 v52, v54
	v_permlane16_swap_b32_e32 v53, v55
	s_waitcnt lgkmcnt(0)
	v_pk_mul_f32 v[50:51], v[50:51], v[48:49] op_sel_hi:[1,0]
	global_store_dwordx4 v[56:57], v[52:55], off offset:256
	s_and_saveexec_b64 s[44:45], vcc
	s_xor_b64 s[44:45], exec, s[44:45]
	v_mov_b32_e32 v44, v51
	s_or_saveexec_b64 s[44:45], s[44:45]
	v_add_u32_e32 v57, 0x90, v145
	v_lshlrev_b32_e32 v40, 4, v57
	s_mov_b32 s6, 0xfdf0
	v_and_or_b32 v40, v40, s6, v144
	v_lshlrev_b32_e32 v56, 3, v40
	global_load_dwordx2 v[244:245], v56, s[22:23]
	global_load_dwordx2 v[246:247], v56, s[22:23] offset:8
	global_load_dwordx2 v[248:249], v56, s[22:23] offset:16
	global_load_dwordx2 v[250:251], v56, s[22:23] offset:24
	s_waitcnt vmcnt(0)
	s_xor_b64 exec, exec, s[44:45]
	s_cbranch_execz .LBB0_670
	v_mov_b32_e32 v52, v244
	v_mov_b32_e32 v53, v245
	v_pk_mul_f32 v[54:55], v[50:51], v[52:53] op_sel:[1,0] op_sel_hi:[0,1]
	v_pk_mul_f32 v[50:51], v[50:51], v[52:53]
	v_sub_f32_e32 v44, v54, v55
	v_add_f32_e32 v50, v50, v51
.LBB0_670:
	s_or_b64 exec, exec, s[44:45]
	v_mov_b32_e32 v49, v48
	v_mov_b32_e32 v40, v45
	v_pk_mul_f32 v[52:53], v[40:41], v[48:49]
	s_and_saveexec_b64 s[44:45], vcc
	s_xor_b64 s[44:45], exec, s[44:45]
	v_mov_b32_e32 v41, v53
	s_andn2_saveexec_b64 s[44:45], s[44:45]
	s_cbranch_execz .LBB0_674
	v_mov_b32_e32 v40, v246
	v_mov_b32_e32 v41, v247
	v_pk_mul_f32 v[54:55], v[52:53], v[40:41] op_sel:[1,0] op_sel_hi:[0,1]
	v_pk_mul_f32 v[40:41], v[52:53], v[40:41]
	s_nop 0
	v_add_f32_e32 v52, v40, v41
	v_sub_f32_e32 v41, v54, v55
.LBB0_674:
	s_or_b64 exec, exec, s[44:45]
	v_mov_b32_e32 v54, v46
	v_mov_b32_e32 v55, v42
	v_pk_mul_f32 v[54:55], v[54:55], v[48:49]
	s_and_saveexec_b64 s[44:45], vcc
	s_xor_b64 s[44:45], exec, s[44:45]
	s_andn2_saveexec_b64 s[44:45], s[44:45]
	s_cbranch_execz .LBB0_676
	v_mov_b32_e32 v58, v248
	v_mov_b32_e32 v59, v249
	v_pk_mul_f32 v[60:61], v[54:55], v[58:59] op_sel:[1,0] op_sel_hi:[0,1]
	v_pk_mul_f32 v[54:55], v[54:55], v[58:59]
	s_nop 0
	v_add_f32_e32 v54, v54, v55
	v_sub_f32_e32 v55, v60, v61
.LBB0_676:
	s_or_b64 exec, exec, s[44:45]
	v_mov_b32_e32 v42, v47
	v_pk_mul_f32 v[42:43], v[42:43], v[48:49]
	s_and_saveexec_b64 s[44:45], vcc
	s_xor_b64 s[44:45], exec, s[44:45]
	s_andn2_saveexec_b64 s[44:45], s[44:45]
	s_cbranch_execz .LBB0_678
	v_mov_b32_e32 v46, v250
	v_mov_b32_e32 v47, v251
	v_pk_mul_f32 v[58:59], v[42:43], v[46:47] op_sel:[1,0] op_sel_hi:[0,1]
	v_pk_mul_f32 v[42:43], v[42:43], v[46:47]
	s_nop 0
	v_add_f32_e32 v42, v42, v43
	v_sub_f32_e32 v43, v58, v59
.LBB0_678:
	s_or_b64 exec, exec, s[44:45]
	v_cvt_pk_bf16_f32 v44, v44, v41
	v_mov_b64_e32 v[40:41], s[40:41]
	v_mad_i64_i32 v[40:41], s[44:45], v57, s59, v[40:41]
	v_lshl_add_u64 v[40:41], v[40:41], 0, v[128:129]
	v_mov_b32_e32 v121, v129
	v_cvt_pk_bf16_f32 v45, v55, v43
	v_cvt_pk_bf16_f32 v46, v50, v52
	v_cvt_pk_bf16_f32 v47, v54, v42
	v_lshl_add_u64 v[40:41], v[40:41], 0, v[120:121]
	v_mov_b32_e32 v123, v129
	v_mov_b32_e32 v42, v36
	v_mov_b32_e32 v43, v32
	v_permlane16_swap_b32_e32 v44, v46
	v_permlane16_swap_b32_e32 v45, v47
	v_lshl_add_u64 v[40:41], v[40:41], 0, v[122:123]
	v_pk_mul_f32 v[42:43], v[42:43], v[48:49]
	global_store_dwordx4 v[40:41], v[44:47], off
	s_and_saveexec_b64 s[44:45], s[2:3]
	s_xor_b64 s[44:45], exec, s[44:45]
	v_mov_b32_e32 v36, v43
	s_andn2_saveexec_b64 s[44:45], s[44:45]
	s_cbranch_execz .LBB0_682
	v_mov_b32_e32 v44, v244
	v_mov_b32_e32 v45, v245
	v_pk_mul_f32 v[46:47], v[42:43], v[44:45] op_sel:[1,0] op_sel_hi:[0,1]
	v_pk_mul_f32 v[42:43], v[42:43], v[44:45]
	v_sub_f32_e32 v36, v46, v47
	v_add_f32_e32 v42, v42, v43
.LBB0_682:
	s_or_b64 exec, exec, s[44:45]
	v_mov_b32_e32 v32, v37
	v_pk_mul_f32 v[44:45], v[32:33], v[48:49]
	s_and_saveexec_b64 s[44:45], s[2:3]
	s_xor_b64 s[44:45], exec, s[44:45]
	v_mov_b32_e32 v33, v45
	s_andn2_saveexec_b64 s[44:45], s[44:45]
	s_cbranch_execz .LBB0_686
	v_mov_b32_e32 v32, v246
	v_mov_b32_e32 v33, v247
	v_pk_mul_f32 v[46:47], v[44:45], v[32:33] op_sel:[1,0] op_sel_hi:[0,1]
	v_pk_mul_f32 v[32:33], v[44:45], v[32:33]
	s_nop 0
	v_add_f32_e32 v44, v32, v33
	v_sub_f32_e32 v33, v46, v47
.LBB0_686:
	s_or_b64 exec, exec, s[44:45]
	v_mov_b32_e32 v46, v38
	v_mov_b32_e32 v47, v34
	v_pk_mul_f32 v[46:47], v[46:47], v[48:49]
	s_and_saveexec_b64 s[44:45], s[2:3]
	s_xor_b64 s[44:45], exec, s[44:45]
	s_andn2_saveexec_b64 s[44:45], s[44:45]
	s_cbranch_execz .LBB0_688
	v_mov_b32_e32 v50, v248
	v_mov_b32_e32 v51, v249
	v_pk_mul_f32 v[52:53], v[46:47], v[50:51] op_sel:[1,0] op_sel_hi:[0,1]
	v_pk_mul_f32 v[46:47], v[46:47], v[50:51]
	s_nop 0
	v_add_f32_e32 v46, v46, v47
	v_sub_f32_e32 v47, v52, v53
.LBB0_688:
	s_or_b64 exec, exec, s[44:45]
	v_mov_b32_e32 v34, v39
	v_pk_mul_f32 v[34:35], v[34:35], v[48:49]
	s_and_saveexec_b64 s[44:45], s[2:3]
	s_xor_b64 s[44:45], exec, s[44:45]
	s_andn2_saveexec_b64 s[44:45], s[44:45]
	s_cbranch_execz .LBB0_692
	v_mov_b32_e32 v38, v250
	v_mov_b32_e32 v39, v251
	v_pk_mul_f32 v[48:49], v[34:35], v[38:39] op_sel:[1,0] op_sel_hi:[0,1]
	v_pk_mul_f32 v[34:35], v[34:35], v[38:39]
	s_nop 0
	v_add_f32_e32 v34, v34, v35
	v_sub_f32_e32 v35, v48, v49
; DEVI void phase2(const Params& p, char* shm) {
;     ...
;           for (int m = 0; m < 4; ++m) {
;             int rl = ai * 128 + wr * 64 + m * 16 + fr;
;             float rs = rsb[rl];
;             int row = brow + rl;
;             int pos = row & 4095;
; #pragma unroll
;             for (int bj = 0; bj < 2; ++bj) {
;               int cA = bcol + bj * 128 + wc * 32;
;               bool isrope = (cA % 96) == 64;
;               f32x4 va = acc[ai][bj][m][0], vb = acc[ai][bj][m][1];
;               float oa[4], ob[4];
; #pragma unroll
;               for (int j = 0; j < 4; ++j) {
;                 float x1 = va[j] * rs, x2 = vb[j] * rs;
;                 if (isrope) {
;                   float2 cs = tab[pos * 16 + fq * 4 + j];
;                   oa[j] = x1 * cs.x - x2 * cs.y;
;                   ob[j] = x1 * cs.y + x2 * cs.x;
;                 } else {
;                   oa[j] = x1;
;                   ob[j] = x2;
;                 }
;               }
;               uint2 pa, pb;
;               pa.x = pack2(oa[0], oa[1]); pa.y = pack2(oa[2], oa[3]);
;               pb.x = pack2(ob[0], ob[1]); pb.y = pack2(ob[2], ob[3]);
;               *reinterpret_cast<uint4*>(Qb + (size_t)row * 768 + cA + (fq & 1) * 16 + (fq >> 1) * 8) = widen_pair(pa, pb);
.LBB0_692:
	s_or_b64 exec, exec, s[44:45]
	ds_read_b32 v32, v143 offset:640
	v_cvt_pk_bf16_f32 v36, v36, v33
	v_cvt_pk_bf16_f32 v37, v47, v35
	v_cvt_pk_bf16_f32 v38, v42, v44
	v_cvt_pk_bf16_f32 v39, v46, v34
	v_mov_b32_e32 v34, v28
	v_mov_b32_e32 v35, v24
	v_permlane16_swap_b32_e32 v36, v38
	v_permlane16_swap_b32_e32 v37, v39
	s_waitcnt lgkmcnt(0)
	v_pk_mul_f32 v[34:35], v[34:35], v[32:33] op_sel_hi:[1,0]
	global_store_dwordx4 v[40:41], v[36:39], off offset:256
	s_and_saveexec_b64 s[44:45], vcc
	s_xor_b64 s[44:45], exec, s[44:45]
	v_mov_b32_e32 v28, v35
	s_or_saveexec_b64 s[44:45], s[44:45]
	v_add_u32_e32 v41, 0xa0, v145
	v_lshlrev_b32_e32 v24, 4, v41
	s_mov_b32 s6, 0xfef0
	v_and_or_b32 v24, v24, s6, v144
	v_lshlrev_b32_e32 v40, 3, v24
	global_load_dwordx2 v[244:245], v40, s[22:23]
	global_load_dwordx2 v[246:247], v40, s[22:23] offset:8
	global_load_dwordx2 v[248:249], v40, s[22:23] offset:16
	global_load_dwordx2 v[250:251], v40, s[22:23] offset:24
	s_waitcnt vmcnt(0)
	s_xor_b64 exec, exec, s[44:45]
	s_cbranch_execz .LBB0_696
	v_mov_b32_e32 v36, v244
	v_mov_b32_e32 v37, v245
	v_pk_mul_f32 v[38:39], v[34:35], v[36:37] op_sel:[1,0] op_sel_hi:[0,1]
	v_pk_mul_f32 v[34:35], v[34:35], v[36:37]
	v_sub_f32_e32 v28, v38, v39
	v_add_f32_e32 v34, v34, v35
.LBB0_696:
	s_or_b64 exec, exec, s[44:45]
	v_mov_b32_e32 v33, v32
	v_mov_b32_e32 v24, v29
	v_pk_mul_f32 v[36:37], v[24:25], v[32:33]
	s_and_saveexec_b64 s[44:45], vcc
	s_xor_b64 s[44:45], exec, s[44:45]
	v_mov_b32_e32 v25, v37
	s_andn2_saveexec_b64 s[44:45], s[44:45]
	s_cbranch_execz .LBB0_700
	v_mov_b32_e32 v24, v246
	v_mov_b32_e32 v25, v247
	v_pk_mul_f32 v[38:39], v[36:37], v[24:25] op_sel:[1,0] op_sel_hi:[0,1]
	v_pk_mul_f32 v[24:25], v[36:37], v[24:25]
	s_nop 0
	v_add_f32_e32 v36, v24, v25
	v_sub_f32_e32 v25, v38, v39
.LBB0_700:
	s_or_b64 exec, exec, s[44:45]
	v_mov_b32_e32 v38, v30
	v_mov_b32_e32 v39, v26
	v_pk_mul_f32 v[38:39], v[38:39], v[32:33]
	s_and_saveexec_b64 s[44:45], vcc
	s_xor_b64 s[44:45], exec, s[44:45]
	s_andn2_saveexec_b64 s[44:45], s[44:45]
	s_cbranch_execz .LBB0_702
	v_mov_b32_e32 v42, v248
	v_mov_b32_e32 v43, v249
	v_pk_mul_f32 v[44:45], v[38:39], v[42:43] op_sel:[1,0] op_sel_hi:[0,1]
	v_pk_mul_f32 v[38:39], v[38:39], v[42:43]
	s_nop 0
	v_add_f32_e32 v38, v38, v39
	v_sub_f32_e32 v39, v44, v45
.LBB0_702:
	s_or_b64 exec, exec, s[44:45]
	v_mov_b32_e32 v26, v31
	v_pk_mul_f32 v[26:27], v[26:27], v[32:33]
	s_and_saveexec_b64 s[44:45], vcc
	s_xor_b64 s[44:45], exec, s[44:45]
	s_andn2_saveexec_b64 s[44:45], s[44:45]
	s_cbranch_execz .LBB0_704
	v_mov_b32_e32 v30, v250
	v_mov_b32_e32 v31, v251
	v_pk_mul_f32 v[42:43], v[26:27], v[30:31] op_sel:[1,0] op_sel_hi:[0,1]
	v_pk_mul_f32 v[26:27], v[26:27], v[30:31]
	s_nop 0
	v_add_f32_e32 v26, v26, v27
	v_sub_f32_e32 v27, v42, v43
.LBB0_704:
	s_or_b64 exec, exec, s[44:45]
	v_cvt_pk_bf16_f32 v28, v28, v25
	v_mov_b64_e32 v[24:25], s[40:41]
	v_mad_i64_i32 v[24:25], s[44:45], v41, s59, v[24:25]
	v_lshl_add_u64 v[24:25], v[24:25], 0, v[128:129]
	v_mov_b32_e32 v121, v129
	v_cvt_pk_bf16_f32 v29, v39, v27
	v_cvt_pk_bf16_f32 v30, v34, v36
	v_cvt_pk_bf16_f32 v31, v38, v26
	v_lshl_add_u64 v[24:25], v[24:25], 0, v[120:121]
	v_mov_b32_e32 v123, v129
	v_mov_b32_e32 v26, v20
	v_mov_b32_e32 v27, v16
	v_permlane16_swap_b32_e32 v28, v30
	v_permlane16_swap_b32_e32 v29, v31
	v_lshl_add_u64 v[24:25], v[24:25], 0, v[122:123]
	v_pk_mul_f32 v[26:27], v[26:27], v[32:33]
	global_store_dwordx4 v[24:25], v[28:31], off
	s_and_saveexec_b64 s[44:45], s[2:3]
	s_xor_b64 s[44:45], exec, s[44:45]
	v_mov_b32_e32 v20, v27
	s_andn2_saveexec_b64 s[44:45], s[44:45]
	s_cbranch_execz .LBB0_708
	v_mov_b32_e32 v28, v244
	v_mov_b32_e32 v29, v245
	v_pk_mul_f32 v[30:31], v[26:27], v[28:29] op_sel:[1,0] op_sel_hi:[0,1]
	v_pk_mul_f32 v[26:27], v[26:27], v[28:29]
	v_sub_f32_e32 v20, v30, v31
	v_add_f32_e32 v26, v26, v27
.LBB0_708:
	s_or_b64 exec, exec, s[44:45]
	v_mov_b32_e32 v16, v21
	v_pk_mul_f32 v[28:29], v[16:17], v[32:33]
	s_and_saveexec_b64 s[44:45], s[2:3]
	s_xor_b64 s[44:45], exec, s[44:45]
	v_mov_b32_e32 v17, v29
	s_andn2_saveexec_b64 s[44:45], s[44:45]
	s_cbranch_execz .LBB0_712
	v_mov_b32_e32 v16, v246
	v_mov_b32_e32 v17, v247
	v_pk_mul_f32 v[30:31], v[28:29], v[16:17] op_sel:[1,0] op_sel_hi:[0,1]
	v_pk_mul_f32 v[16:17], v[28:29], v[16:17]
	s_nop 0
	v_add_f32_e32 v28, v16, v17
	v_sub_f32_e32 v17, v30, v31
.LBB0_712:
	s_or_b64 exec, exec, s[44:45]
	v_mov_b32_e32 v30, v22
	v_mov_b32_e32 v31, v18
	v_pk_mul_f32 v[30:31], v[30:31], v[32:33]
	s_and_saveexec_b64 s[44:45], s[2:3]
	s_xor_b64 s[44:45], exec, s[44:45]
	s_andn2_saveexec_b64 s[44:45], s[44:45]
	s_cbranch_execz .LBB0_714
	v_mov_b32_e32 v34, v248
	v_mov_b32_e32 v35, v249
	v_pk_mul_f32 v[36:37], v[30:31], v[34:35] op_sel:[1,0] op_sel_hi:[0,1]
	v_pk_mul_f32 v[30:31], v[30:31], v[34:35]
	s_nop 0
	v_add_f32_e32 v30, v30, v31
	v_sub_f32_e32 v31, v36, v37
.LBB0_714:
	s_or_b64 exec, exec, s[44:45]
	v_mov_b32_e32 v18, v23
	v_pk_mul_f32 v[18:19], v[18:19], v[32:33]
	s_and_saveexec_b64 s[44:45], s[2:3]
	s_xor_b64 s[44:45], exec, s[44:45]
	s_andn2_saveexec_b64 s[44:45], s[44:45]
	s_cbranch_execz .LBB0_718
	v_mov_b32_e32 v22, v250
	v_mov_b32_e32 v23, v251
	v_pk_mul_f32 v[32:33], v[18:19], v[22:23] op_sel:[1,0] op_sel_hi:[0,1]
	v_pk_mul_f32 v[18:19], v[18:19], v[22:23]
	s_nop 0
	v_add_f32_e32 v18, v18, v19
	v_sub_f32_e32 v19, v32, v33
; DEVI void phase2(const Params& p, char* shm) {
;     ...
;           for (int m = 0; m < 4; ++m) {
;             int rl = ai * 128 + wr * 64 + m * 16 + fr;
;             float rs = rsb[rl];
;             int row = brow + rl;
;             int pos = row & 4095;
; #pragma unroll
;             for (int bj = 0; bj < 2; ++bj) {
;               int cA = bcol + bj * 128 + wc * 32;
;               bool isrope = (cA % 96) == 64;
;               f32x4 va = acc[ai][bj][m][0], vb = acc[ai][bj][m][1];
;               float oa[4], ob[4];
; #pragma unroll
;               for (int j = 0; j < 4; ++j) {
;                 float x1 = va[j] * rs, x2 = vb[j] * rs;
;                 if (isrope) {
;                   float2 cs = tab[pos * 16 + fq * 4 + j];
;                   oa[j] = x1 * cs.x - x2 * cs.y;
;                   ob[j] = x1 * cs.y + x2 * cs.x;
;                 } else {
;                   oa[j] = x1;
;                   ob[j] = x2;
;                 }
;               }
;               uint2 pa, pb;
;               pa.x = pack2(oa[0], oa[1]); pa.y = pack2(oa[2], oa[3]);
;               pb.x = pack2(ob[0], ob[1]); pb.y = pack2(ob[2], ob[3]);
;               *reinterpret_cast<uint4*>(Qb + (size_t)row * 768 + cA + (fq & 1) * 16 + (fq >> 1) * 8) = widen_pair(pa, pb);
.LBB0_718:
	s_or_b64 exec, exec, s[44:45]
	ds_read_b32 v16, v143 offset:704
	v_cvt_pk_bf16_f32 v20, v20, v17
	v_cvt_pk_bf16_f32 v21, v31, v19
	v_cvt_pk_bf16_f32 v22, v26, v28
	v_cvt_pk_bf16_f32 v23, v30, v18
	v_mov_b32_e32 v18, v12
	v_mov_b32_e32 v19, v8
	v_permlane16_swap_b32_e32 v20, v22
	v_permlane16_swap_b32_e32 v21, v23
	s_waitcnt lgkmcnt(0)
	v_pk_mul_f32 v[18:19], v[18:19], v[16:17] op_sel_hi:[1,0]
	global_store_dwordx4 v[24:25], v[20:23], off offset:256
	s_and_saveexec_b64 s[44:45], vcc
	s_xor_b64 s[44:45], exec, s[44:45]
	v_mov_b32_e32 v12, v19
	s_or_saveexec_b64 s[44:45], s[44:45]
	v_add_u32_e32 v25, 0xb0, v145
	v_lshlrev_b32_e32 v8, 4, v25
	v_and_or_b32 v8, v8, s71, v144
	v_lshlrev_b32_e32 v24, 3, v8
	global_load_dwordx2 v[244:245], v24, s[22:23]
	global_load_dwordx2 v[246:247], v24, s[22:23] offset:8
	global_load_dwordx2 v[248:249], v24, s[22:23] offset:16
	global_load_dwordx2 v[250:251], v24, s[22:23] offset:24
	s_waitcnt vmcnt(0)
	s_xor_b64 exec, exec, s[44:45]
	s_cbranch_execz .LBB0_722
	v_mov_b32_e32 v20, v244
	v_mov_b32_e32 v21, v245
	v_pk_mul_f32 v[22:23], v[18:19], v[20:21] op_sel:[1,0] op_sel_hi:[0,1]
	v_pk_mul_f32 v[18:19], v[18:19], v[20:21]
	v_sub_f32_e32 v12, v22, v23
	v_add_f32_e32 v18, v18, v19
.LBB0_722:
	s_or_b64 exec, exec, s[44:45]
	v_mov_b32_e32 v17, v16
	v_mov_b32_e32 v8, v13
	v_pk_mul_f32 v[20:21], v[8:9], v[16:17]
	s_and_saveexec_b64 s[44:45], vcc
	s_xor_b64 s[44:45], exec, s[44:45]
	v_mov_b32_e32 v9, v21
	s_andn2_saveexec_b64 s[44:45], s[44:45]
	s_cbranch_execz .LBB0_726
	v_mov_b32_e32 v8, v246
	v_mov_b32_e32 v9, v247
	v_pk_mul_f32 v[22:23], v[20:21], v[8:9] op_sel:[1,0] op_sel_hi:[0,1]
	v_pk_mul_f32 v[8:9], v[20:21], v[8:9]
	s_nop 0
	v_add_f32_e32 v20, v8, v9
	v_sub_f32_e32 v9, v22, v23
.LBB0_726:
	s_or_b64 exec, exec, s[44:45]
	v_mov_b32_e32 v22, v14
	v_mov_b32_e32 v23, v10
	v_pk_mul_f32 v[22:23], v[22:23], v[16:17]
	s_and_saveexec_b64 s[44:45], vcc
	s_xor_b64 s[44:45], exec, s[44:45]
	s_andn2_saveexec_b64 s[44:45], s[44:45]
	s_cbranch_execz .LBB0_728
	v_mov_b32_e32 v26, v248
	v_mov_b32_e32 v27, v249
	v_pk_mul_f32 v[28:29], v[22:23], v[26:27] op_sel:[1,0] op_sel_hi:[0,1]
	v_pk_mul_f32 v[22:23], v[22:23], v[26:27]
	s_nop 0
	v_add_f32_e32 v22, v22, v23
	v_sub_f32_e32 v23, v28, v29
.LBB0_728:
	s_or_b64 exec, exec, s[44:45]
	v_mov_b32_e32 v10, v15
	v_pk_mul_f32 v[10:11], v[10:11], v[16:17]
	s_and_saveexec_b64 s[44:45], vcc
	s_xor_b64 s[44:45], exec, s[44:45]
	s_andn2_saveexec_b64 s[44:45], s[44:45]
	s_cbranch_execz .LBB0_730
	v_mov_b32_e32 v14, v250
	v_mov_b32_e32 v15, v251
	v_pk_mul_f32 v[26:27], v[10:11], v[14:15] op_sel:[1,0] op_sel_hi:[0,1]
	v_pk_mul_f32 v[10:11], v[10:11], v[14:15]
	s_nop 0
	v_add_f32_e32 v10, v10, v11
	v_sub_f32_e32 v11, v26, v27
.LBB0_730:
	s_or_b64 exec, exec, s[44:45]
	v_cvt_pk_bf16_f32 v12, v12, v9
	v_mov_b64_e32 v[8:9], s[40:41]
	v_mad_i64_i32 v[8:9], s[44:45], v25, s59, v[8:9]
	v_lshl_add_u64 v[8:9], v[8:9], 0, v[128:129]
	v_mov_b32_e32 v121, v129
	v_cvt_pk_bf16_f32 v13, v23, v11
	v_cvt_pk_bf16_f32 v14, v18, v20
	v_cvt_pk_bf16_f32 v15, v22, v10
	v_lshl_add_u64 v[8:9], v[8:9], 0, v[120:121]
	v_mov_b32_e32 v123, v129
	v_mov_b32_e32 v10, v4
	v_mov_b32_e32 v11, v0
	v_permlane16_swap_b32_e32 v12, v14
	v_permlane16_swap_b32_e32 v13, v15
	v_lshl_add_u64 v[8:9], v[8:9], 0, v[122:123]
	v_pk_mul_f32 v[10:11], v[10:11], v[16:17]
	global_store_dwordx4 v[8:9], v[12:15], off
	s_and_saveexec_b64 s[44:45], s[2:3]
	s_xor_b64 s[44:45], exec, s[44:45]
	v_mov_b32_e32 v4, v11
	s_andn2_saveexec_b64 s[44:45], s[44:45]
	s_cbranch_execz .LBB0_734
	v_mov_b32_e32 v12, v244
	v_mov_b32_e32 v13, v245
	v_pk_mul_f32 v[14:15], v[10:11], v[12:13] op_sel:[1,0] op_sel_hi:[0,1]
	v_pk_mul_f32 v[10:11], v[10:11], v[12:13]
	v_sub_f32_e32 v4, v14, v15
	v_add_f32_e32 v10, v10, v11
.LBB0_734:
	s_or_b64 exec, exec, s[44:45]
	v_mov_b32_e32 v0, v5
	v_pk_mul_f32 v[12:13], v[0:1], v[16:17]
	s_and_saveexec_b64 s[44:45], s[2:3]
	s_xor_b64 s[44:45], exec, s[44:45]
	v_mov_b32_e32 v1, v13
	s_andn2_saveexec_b64 s[44:45], s[44:45]
	s_cbranch_execz .LBB0_738
	v_mov_b32_e32 v0, v246
	v_mov_b32_e32 v1, v247
	v_pk_mul_f32 v[14:15], v[12:13], v[0:1] op_sel:[1,0] op_sel_hi:[0,1]
	v_pk_mul_f32 v[0:1], v[12:13], v[0:1]
	s_nop 0
	v_add_f32_e32 v12, v0, v1
	v_sub_f32_e32 v1, v14, v15
.LBB0_738:
	s_or_b64 exec, exec, s[44:45]
	v_mov_b32_e32 v14, v6
	v_mov_b32_e32 v15, v2
	v_pk_mul_f32 v[14:15], v[14:15], v[16:17]
	s_and_saveexec_b64 s[44:45], s[2:3]
	s_xor_b64 s[44:45], exec, s[44:45]
	s_andn2_saveexec_b64 s[44:45], s[44:45]
	s_cbranch_execz .LBB0_740
	v_mov_b32_e32 v18, v248
	v_mov_b32_e32 v19, v249
	v_pk_mul_f32 v[20:21], v[14:15], v[18:19] op_sel:[1,0] op_sel_hi:[0,1]
	v_pk_mul_f32 v[14:15], v[14:15], v[18:19]
	s_nop 0
	v_add_f32_e32 v14, v14, v15
	v_sub_f32_e32 v15, v20, v21
.LBB0_740:
	s_or_b64 exec, exec, s[44:45]
	v_mov_b32_e32 v2, v7
	v_pk_mul_f32 v[2:3], v[2:3], v[16:17]
	s_and_saveexec_b64 s[44:45], s[2:3]
	s_xor_b64 s[2:3], exec, s[44:45]
	s_andn2_saveexec_b64 s[2:3], s[2:3]
	s_cbranch_execz .LBB0_744
	v_mov_b32_e32 v6, v250
	v_mov_b32_e32 v7, v251
	v_pk_mul_f32 v[16:17], v[2:3], v[6:7] op_sel:[1,0] op_sel_hi:[0,1]
	v_pk_mul_f32 v[2:3], v[2:3], v[6:7]
	s_nop 0
	v_add_f32_e32 v2, v2, v3
	v_sub_f32_e32 v3, v16, v17

; DEVI void ph_lnrouter(const Params& p, int layer, char* shm) {
;     ...
;   for (int i = tid; i < 4096; i += NTHR) {
;     float4 v = *reinterpret_cast<const float4*>(wrt + (size_t)i * 4);
;     int c = i >> 2, e0 = (i & 3) * 4;
;     Wt[(e0 + 0) * 1024 + c] = v.x;
;     Wt[(e0 + 1) * 1024 + c] = v.y;
;     Wt[(e0 + 2) * 1024 + c] = v.z;
;     Wt[(e0 + 3) * 1024 + c] = v.w;
;   }
.LBB0_1068:
	v_and_b32_e32 v5, 0x3000, v4
	v_and_b32_e32 v10, -4, v1
	v_lshlrev_b32_e32 v5, 2, v5
	v_add3_u32 v5, 0, v5, v10
	global_load_dwordx4 v[12:15], v[2:3], off offset:-8
	v_lshl_add_u64 v[2:3], v[2:3], 0, s[4:5]
	global_load_dwordx4 v[16:19], v[2:3], off offset:-8
	v_lshl_add_u64 v[2:3], v[2:3], 0, s[4:5]
	global_load_dwordx4 v[20:23], v[2:3], off offset:-8
	v_lshl_add_u64 v[2:3], v[2:3], 0, s[4:5]
	global_load_dwordx4 v[24:27], v[2:3], off offset:-8
	v_lshl_add_u64 v[2:3], v[2:3], 0, s[4:5]
	global_load_dwordx4 v[28:31], v[2:3], off offset:-8
	v_lshl_add_u64 v[2:3], v[2:3], 0, s[4:5]
	global_load_dwordx4 v[32:35], v[2:3], off offset:-8
	v_lshl_add_u64 v[2:3], v[2:3], 0, s[4:5]
	global_load_dwordx4 v[36:39], v[2:3], off offset:-8
	v_lshl_add_u64 v[2:3], v[2:3], 0, s[4:5]
	global_load_dwordx4 v[40:43], v[2:3], off offset:-8
	s_waitcnt vmcnt(7)
	ds_write2st64_b32 v5, v12, v13 offset0:0 offset1:16
	ds_write2st64_b32 v5, v14, v15 offset0:32 offset1:48
	s_waitcnt vmcnt(6)
	ds_write2st64_b32 v5, v16, v17 offset0:2 offset1:18
	ds_write2st64_b32 v5, v18, v19 offset0:34 offset1:50
	s_waitcnt vmcnt(5)
	ds_write2st64_b32 v5, v20, v21 offset0:4 offset1:20
	ds_write2st64_b32 v5, v22, v23 offset0:36 offset1:52
	s_waitcnt vmcnt(4)
	ds_write2st64_b32 v5, v24, v25 offset0:6 offset1:22
	ds_write2st64_b32 v5, v26, v27 offset0:38 offset1:54
	s_waitcnt vmcnt(3)
	ds_write2st64_b32 v5, v28, v29 offset0:8 offset1:24
	ds_write2st64_b32 v5, v30, v31 offset0:40 offset1:56
	s_waitcnt vmcnt(2)
	ds_write2st64_b32 v5, v32, v33 offset0:10 offset1:26
	ds_write2st64_b32 v5, v34, v35 offset0:42 offset1:58
	s_waitcnt vmcnt(1)
	ds_write2st64_b32 v5, v36, v37 offset0:12 offset1:28
	ds_write2st64_b32 v5, v38, v39 offset0:44 offset1:60
	s_waitcnt vmcnt(0)
	ds_write2st64_b32 v5, v40, v41 offset0:14 offset1:30
	ds_write2st64_b32 v5, v42, v43 offset0:46 offset1:62
